# v28 + lever 4: one static s_setprio 1 for waves 4-7 before the LRU item loops and the attention loop (reset at the grid barrier)
# speedup vs baseline: 1.0013x; 1.0013x over previous
; template <int PASS>
; __device__ void lru_items(const Params& p, unsigned char* shm, int l) {
;     bf16_t* xraw = (bf16_t*)shm;
;     float* xcf = (float*)(shm + 8704);
;     bf16_t* xcb = (bf16_t*)(shm + 25344);
;     bf16_t* wt = (bf16_t*)(shm + 34560);
;     float* As = (float*)(shm + 71424);
;     float* Bs = (float*)(shm + 104192);
;     float* Pq = (float*)(shm + 136960);
;     float* Hq = (float*)(shm + 139008);
;     const bf16_t* XL = (const bf16_t*)(p.ws + B_XL); bf16_t* GL = (bf16_t*)(p.ws + B_GL); const bf16_t* LWT = (const bf16_t*)(p.ws + SM_LWT);
;     float* SA = (float*)(p.ws + SM_SA); float* SH = (float*)(p.ws + SM_SH); const float* CIN = (const float*)(p.ws + SM_CIN);
;     const float* cw = p.in[4] + l * 4096; const float* cbias = p.in[5] + l * 1024;
;     const int tid = ltid(p.wave), lane = tid & 63, w = tid >> 6, fr = lane & 15, fq = lane >> 4, G_ = gridDim.x, total = NCHK * 16;
;     int n_loaded = -1;
;     float c0 = 0.f, c1 = 0.f, c2 = 0.f, c3 = 0.f, cb = 0.f, gba[4], gbx[4], gsp[4];
; #pragma unroll
;     for (int jt = 0; jt < 4; ++jt) { gba[jt] = 0.f; gbx[jt] = 0.f; gsp[jt] = 0.f; }
;     u32x4 xr0 = (u32x4){0u, 0u, 0u, 0u}, xr1 = (u32x4){0u, 0u, 0u, 0u};
;     ...
;     int it = lbid();
;     if (it < total) LRU_LOAD(it);
;     for (; it < total; it += G_) {
;         const int ck = it >> 4, n = it & 15, t0 = ck * 64;
;         *(u32x4*)(xraw + (tid >> 3) * 64 + (tid & 7) * 8) = xr0;
;         if (tid < 24) *(u32x4*)(xraw + (64 + (tid >> 3)) * 64 + (tid & 7) * 8) = xr1;
;         if (n != n_loaded) {
;             n_loaded = n;
; #pragma unroll
;             for (int i = 0; i < 4; ++i) { const int e = tid + 512 * i, mtx = e >> 9, rem = e & 511, j = rem >> 3, c8 = rem & 7;
;                 *(u32x4*)(wt + (mtx * 64 + j) * 72 + c8 * 8) = *(const u32x4*)(LWT + ((size_t)(mtx * 16 + n) * 64 + j) * 64 + c8 * 8); }
;             { const int ch = n * 64 + (tid & 63); c0 = cw[ch]; c1 = cw[1024 + ch]; c2 = cw[2048 + ch]; c3 = cw[3072 + ch]; cb = cbias[ch]; }
; #pragma unroll
;             for (int jt = 0; jt < 4; ++jt) { const int pi = (l * 2 + (w >> 2)) * 1024 + n * 64 + jt * 16 + fr; gba[jt] = p.in[7][pi]; gbx[jt] = p.in[9][pi]; gsp[jt] = -8.0f * log1pf(__expf(-p.in[10][pi])); }
;         }
;         u32x4 glv = (u32x4){0u, 0u, 0u, 0u}; float cin = 0.f;
;         const size_t go = (size_t)(t0 + (tid >> 3)) * 1024 + n * 64 + (tid & 7) * 8;
.LBB0_198:
	s_or_b64 exec, exec, s[0:1]
	v_readlane_b32 s0, v254, 43
	v_readlane_b32 s1, v254, 44
	s_mov_b32 s6, s0
	s_lshl_b32 s0, s0, 12
	s_ashr_i32 s1, s0, 31
	s_lshl_b32 s4, s6, 10
	v_readlane_b32 s60, v251, 20
	s_ashr_i32 s5, s4, 31
	s_lshl_b64 s[0:1], s[0:1], 2
	v_readlane_b32 s68, v251, 28
	v_readlane_b32 s61, v251, 21
	v_readlane_b32 s69, v251, 29
	s_add_u32 s60, s68, s0
	v_readlane_b32 s62, v251, 22
	v_readlane_b32 s70, v251, 30
	s_addc_u32 s61, s69, s1
	s_lshl_b64 s[0:1], s[4:5], 2
	v_readlane_b32 s63, v251, 23
	v_readlane_b32 s71, v251, 31
	s_add_u32 s62, s70, s0
	s_addc_u32 s63, s71, s1
	v_lshlrev_b32_e32 v0, 3, v142
	v_bfe_u32 v17, v142, 3, 6
	v_readlane_b32 s0, v252, 11
	v_and_b32_e32 v26, 56, v0
	v_lshlrev_b32_e32 v0, 7, v17
	v_readlane_b32 s1, v252, 12
	v_lshlrev_b32_e32 v10, 1, v26
	v_mov_b32_e32 v11, v1
	v_lshl_add_u64 v[12:13], s[0:1], 0, v[0:1]
	v_add_u32_e32 v16, 0, v10
	v_lshl_add_u64 v[28:29], v[12:13], 0, v[10:11]
	v_lshlrev_b32_e32 v10, 2, v142
	v_and_b32_e32 v0, 0xfffffc00, v10
	v_and_b32_e32 v43, 63, v142
	v_and_b32_e32 v14, 15, v142
	v_lshl_add_u32 v0, s6, 11, v0
	v_readlane_b32 s0, v252, 15
	v_lshlrev_b32_e32 v25, 8, v27
	v_lshlrev_b32_e32 v32, 2, v26
	v_readlane_b32 s4, v254, 6
	v_add_u32_e32 v33, 0x200, v142
	v_add_u32_e32 v34, 0x400, v142
	v_add_u32_e32 v35, 0x600, v142
	v_or_b32_e32 v45, v0, v14
	v_lshlrev_b32_e32 v0, 2, v43
	v_readlane_b32 s1, v252, 16
	v_add3_u32 v50, s4, v25, v32
	v_ashrrev_i32_e32 v32, 9, v142
	v_ashrrev_i32_e32 v33, 9, v33
	v_ashrrev_i32_e32 v34, 9, v34
	v_ashrrev_i32_e32 v35, 9, v35
	v_lshl_add_u64 v[30:31], s[0:1], 0, v[0:1]
	v_lshlrev_b32_e32 v0, 1, v43
	v_lshlrev_b32_e32 v52, 4, v32
	v_lshl_or_b32 v32, v32, 6, v17
	v_lshlrev_b32_e32 v53, 4, v33
	v_lshl_or_b32 v33, v33, 6, v17
	v_lshlrev_b32_e32 v54, 4, v34
	v_lshl_or_b32 v34, v34, 6, v17
	v_lshlrev_b32_e32 v55, 4, v35
	v_lshl_or_b32 v17, v35, 6, v17
	v_lshlrev_b32_e32 v35, 1, v142
	v_ashrrev_i32_e32 v15, 6, v142
	v_add_u32_e32 v11, 0, v0
	s_movk_i32 s0, 0x90
	v_and_b32_e32 v35, 0xffffff80, v35
	s_movk_i32 s6, 0x104
	v_and_b32_e32 v46, 1, v15
	v_lshlrev_b32_e32 v18, 4, v15
	v_add_u32_e32 v56, v11, v35
	v_add3_u32 v57, 0, v35, v0
	v_mul_lo_u32 v35, v15, s6
	v_mul_lo_u32 v36, v15, s0
	v_lshlrev_b32_e32 v15, 7, v15
	v_add_u32_e32 v37, 0x400, v15
	v_add_u32_e32 v58, v11, v37
	v_add3_u32 v59, 0, v37, v0
	v_add_u32_e32 v37, 0x800, v15
	v_add_u32_e32 v60, v11, v37
	v_add3_u32 v61, 0, v37, v0
	v_add_u32_e32 v37, 0xc00, v15
	v_and_b32_e32 v18, 48, v18
	v_and_b32_e32 v20, 48, v142
	v_add_u32_e32 v62, v11, v37
	v_add3_u32 v63, 0, v37, v0
	v_add_u32_e32 v37, 0x1000, v15
	v_ashrrev_i32_e32 v13, 8, v142
	v_or_b32_e32 v19, v18, v14
	v_add_u32_e32 v21, 0, v20
	v_add_u32_e32 v64, v11, v37
	v_add3_u32 v65, 0, v37, v0
	v_add_u32_e32 v37, 0x1400, v15
	v_mad_u32_u24 v47, v19, s0, v21
	v_lshl_or_b32 v19, v13, 7, v14
	v_lshrrev_b32_e32 v22, 2, v142
	v_add_u32_e32 v66, v11, v37
	v_add3_u32 v67, 0, v37, v0
	v_add_u32_e32 v37, 0x1800, v15
	v_add_u32_e32 v15, 0x1c00, v15
	v_add_u32_e32 v12, v11, v0
	v_and_or_b32 v18, v22, 12, v18
	v_lshlrev_b32_e32 v13, 12, v13
	v_add3_u32 v69, 0, v37, v0
	v_add3_u32 v71, 0, v15, v0
	v_mul_lo_u32 v0, v19, s0
	v_add_u32_e32 v72, v21, v0
	v_add3_u32 v73, 0, v0, v20
	v_lshl_or_b32 v0, v18, 6, v13
	v_or_b32_e32 v13, v0, v14
	v_readlane_b32 s5, v254, 7
	v_lshlrev_b32_e32 v13, 2, v13
	v_add_u32_e32 v75, s4, v13
	v_add_u32_e32 v74, s5, v13
	v_or_b32_e32 v13, 64, v0
	v_or_b32_e32 v19, v13, v14
	v_lshlrev_b32_e32 v19, 2, v19
	v_add_u32_e32 v76, s5, v19
	v_add_u32_e32 v77, s4, v19
	v_or_b32_e32 v19, 0x80, v0
	v_or_b32_e32 v20, v19, v14
	v_lshlrev_b32_e32 v20, 2, v20
	v_add_u32_e32 v78, s5, v20
	v_add_u32_e32 v79, s4, v20
	v_or_b32_e32 v20, 0xc0, v0
	v_or_b32_e32 v21, v20, v14
	v_lshlrev_b32_e32 v21, 2, v21
	v_add_u32_e32 v80, s5, v21
	v_add_u32_e32 v81, s4, v21
	v_or_b32_e32 v21, 16, v14
	v_add_u32_e32 v68, v11, v37
	v_or_b32_e32 v37, v0, v21
	v_lshlrev_b32_e32 v37, 2, v37
	v_add_u32_e32 v82, s5, v37
	v_add_u32_e32 v83, s4, v37
	v_or_b32_e32 v37, v13, v21
	v_lshlrev_b32_e32 v37, 2, v37
	v_add_u32_e32 v84, s5, v37
	v_add_u32_e32 v85, s4, v37
	v_or_b32_e32 v37, v19, v21
	v_or_b32_e32 v21, v20, v21
	v_lshlrev_b32_e32 v21, 2, v21
	v_add_u32_e32 v70, v11, v15
	v_lshl_add_u32 v15, v14, 2, 0
	v_lshlrev_b32_e32 v37, 2, v37
	v_add_u32_e32 v88, s5, v21
	v_add_u32_e32 v89, s4, v21
	v_or_b32_e32 v21, 32, v14
	v_or_b32_e32 v14, 48, v14
	v_add_u32_e32 v86, s5, v37
	v_add_u32_e32 v87, s4, v37
	v_or_b32_e32 v37, v0, v21
	v_or_b32_e32 v0, v0, v14
	v_lshlrev_b32_e32 v0, 2, v0
	v_add_u32_e32 v98, s5, v0
	v_add_u32_e32 v99, s4, v0
	v_or_b32_e32 v0, v13, v14
	v_lshlrev_b32_e32 v0, 2, v0
	v_add_u32_e32 v100, s5, v0
	v_add_u32_e32 v101, s4, v0
	v_or_b32_e32 v0, v19, v14
	v_lshlrev_b32_e32 v0, 2, v0
	v_ashrrev_i32_e32 v22, 7, v142
	v_add_u32_e32 v102, s5, v0
	v_add_u32_e32 v103, s4, v0
	v_or_b32_e32 v0, v20, v14
	v_lshlrev_b32_e32 v23, 4, v22
	v_lshlrev_b32_e32 v0, 2, v0
	v_lshlrev_b32_e32 v37, 2, v37
	v_add_u32_e32 v104, s5, v0
	v_add_u32_e32 v105, s4, v0
	v_or_b32_e32 v0, 1, v23
	v_cmp_eq_u32_e32 vcc, 0, v46
	v_add_u32_e32 v90, s5, v37
	v_add_u32_e32 v91, s4, v37
	v_or_b32_e32 v37, v13, v21
	v_sub_u32_e32 v13, 63, v0
	v_cndmask_b32_e32 v0, v13, v0, vcc
; __device__ __forceinline__ int ltid(int wave) { int t = (wave << 6) | (int)__builtin_amdgcn_mbcnt_hi(~0u, __builtin_amdgcn_mbcnt_lo(~0u, 0u)); asm volatile("" : "+v"(t)); return t; }
; __device__ __forceinline__ int lbid() { int b = blockIdx.x; asm volatile("" : "+s"(b)); return b; }
; template <int PASS>
; __device__ void lru_items(const Params& p, unsigned char* shm, int l) {
;     ...
;     const int tid = ltid(p.wave), lane = tid & 63, w = tid >> 6, fr = lane & 15, fq = lane >> 4, G_ = gridDim.x, total = NCHK * 16;
;     int n_loaded = -1;
;     float c0 = 0.f, c1 = 0.f, c2 = 0.f, c3 = 0.f, cb = 0.f, gba[4], gbx[4], gsp[4];
; #pragma unroll
;     for (int jt = 0; jt < 4; ++jt) { gba[jt] = 0.f; gbx[jt] = 0.f; gsp[jt] = 0.f; }
;     u32x4 xr0 = (u32x4){0u, 0u, 0u, 0u}, xr1 = (u32x4){0u, 0u, 0u, 0u};
;     ...
;     int it = lbid();
;     if (it < total) LRU_LOAD(it);
;     for (; it < total; it += G_) {
;     ...
;             const int seg = tid >> 7, d = (tid >> 6) & 1, j = tid & 63;
;             float h = 0.f, P = 1.f;
; #pragma unroll
;             for (int s = 0; s < 16; ++s) { const int st = seg * 16 + s, t = d ? 63 - st : st; const float a = As[(d * 64 + t) * 64 + j]; h = a * h + Bs[(d * 64 + t) * 64 + j]; P *= a; }
;             Pq[seg * 128 + (tid & 127)] = P; Hq[seg * 128 + (tid & 127)] = h;
;             __syncthreads();
;             if (PASS == 0) {
;                 if (tid < 128) { float hh = Hq[tid], PP = Pq[tid];
; #pragma unroll
;                     for (int q = 1; q < 4; ++q) { const float pq = Pq[q * 128 + tid]; hh = pq * hh + Hq[q * 128 + tid]; PP *= pq; }
;                     SA[so] = PP; SH[so] = hh; }
;             } else {
;                 float c = cin;
; #pragma unroll
;                 for (int q = 0; q < 3; ++q) if (q < seg) c = Pq[q * 128 + (tid & 127)] * c + Hq[q * 128 + (tid & 127)];
; #pragma unroll
;                 for (int s = 0; s < 16; ++s) { const int st = seg * 16 + s, t = d ? 63 - st : st; c = As[(d * 64 + t) * 64 + j] * c + Bs[(d * 64 + t) * 64 + j]; Bs[(d * 64 + t) * 64 + j] = c; }
	v_lshl_or_b32 v24, v46, 12, v43
	v_lshlrev_b32_e32 v0, 6, v0
	v_add_lshl_u32 v0, v0, v24, 2
	v_add_u32_e32 v107, s5, v0
	v_add_u32_e32 v108, s4, v0
	v_or_b32_e32 v0, 2, v23
	v_sub_u32_e32 v13, 63, v0
	v_cndmask_b32_e32 v0, v13, v0, vcc
	v_lshlrev_b32_e32 v0, 6, v0
	v_add_lshl_u32 v0, v0, v24, 2
	v_add_u32_e32 v109, s5, v0
	v_add_u32_e32 v110, s4, v0
	v_or_b32_e32 v0, 3, v23
	v_sub_u32_e32 v13, 63, v0
	v_cndmask_b32_e32 v0, v13, v0, vcc
	v_lshlrev_b32_e32 v0, 6, v0
	v_add_lshl_u32 v0, v0, v24, 2
	v_add_u32_e32 v111, s5, v0
	v_add_u32_e32 v112, s4, v0
	v_or_b32_e32 v0, 4, v23
	v_sub_u32_e32 v13, 63, v0
	v_cndmask_b32_e32 v0, v13, v0, vcc
	v_lshlrev_b32_e32 v0, 6, v0
	v_add_lshl_u32 v0, v0, v24, 2
	v_add_u32_e32 v113, s5, v0
	v_add_u32_e32 v114, s4, v0
	v_or_b32_e32 v0, 5, v23
	v_sub_u32_e32 v13, 63, v0
	v_cndmask_b32_e32 v0, v13, v0, vcc
	v_lshlrev_b32_e32 v0, 6, v0
	v_add_lshl_u32 v0, v0, v24, 2
	v_add_u32_e32 v115, s5, v0
	v_add_u32_e32 v116, s4, v0
	v_or_b32_e32 v0, 6, v23
	v_sub_u32_e32 v13, 63, v0
	v_cndmask_b32_e32 v0, v13, v0, vcc
	v_lshlrev_b32_e32 v0, 6, v0
	v_add_lshl_u32 v0, v0, v24, 2
	v_add_u32_e32 v117, s5, v0
	v_add_u32_e32 v118, s4, v0
	v_or_b32_e32 v0, 7, v23
	v_sub_u32_e32 v13, 63, v0
	v_cndmask_b32_e32 v0, v13, v0, vcc
	v_lshlrev_b32_e32 v0, 6, v0
	v_add_lshl_u32 v0, v0, v24, 2
	v_add_u32_e32 v119, s5, v0
	v_add_u32_e32 v120, s4, v0
	v_or_b32_e32 v0, 8, v23
	v_sub_u32_e32 v13, 63, v0
	v_cndmask_b32_e32 v0, v13, v0, vcc
	v_lshlrev_b32_e32 v0, 6, v0
	v_add_lshl_u32 v0, v0, v24, 2
	v_add_u32_e32 v121, s5, v0
	v_add_u32_e32 v122, s4, v0
	v_or_b32_e32 v0, 9, v23
	v_sub_u32_e32 v13, 63, v0
	v_cndmask_b32_e32 v0, v13, v0, vcc
	v_lshlrev_b32_e32 v0, 6, v0
	v_add_lshl_u32 v0, v0, v24, 2
	v_add_u32_e32 v123, s5, v0
	v_add_u32_e32 v124, s4, v0
	v_or_b32_e32 v0, 10, v23
	v_sub_u32_e32 v13, 63, v0
	v_cndmask_b32_e32 v0, v13, v0, vcc
	v_lshlrev_b32_e32 v0, 6, v0
	v_add_lshl_u32 v0, v0, v24, 2
	v_add_u32_e32 v125, s5, v0
	v_add_u32_e32 v126, s4, v0
	v_or_b32_e32 v0, 11, v23
	v_sub_u32_e32 v13, 63, v0
	v_cndmask_b32_e32 v0, v13, v0, vcc
	v_lshlrev_b32_e32 v0, 6, v0
	v_add_lshl_u32 v0, v0, v24, 2
	v_add_u32_e32 v127, s5, v0
	v_add_u32_e32 v128, s4, v0
	v_or_b32_e32 v0, 12, v23
	v_sub_u32_e32 v13, 63, v0
	v_cndmask_b32_e32 v0, v13, v0, vcc
	v_lshlrev_b32_e32 v0, 6, v0
	v_add_lshl_u32 v0, v0, v24, 2
	v_add_u32_e32 v129, s5, v0
	v_add_u32_e32 v130, s4, v0
	v_or_b32_e32 v0, 13, v23
	v_sub_u32_e32 v13, 63, v0
	v_cndmask_b32_e32 v0, v13, v0, vcc
	v_lshlrev_b32_e32 v0, 6, v0
	v_add_lshl_u32 v0, v0, v24, 2
	v_add_u32_e32 v131, s5, v0
	v_add_u32_e32 v132, s4, v0
	v_or_b32_e32 v0, 14, v23
	v_sub_u32_e32 v13, 63, v0
	v_cndmask_b32_e32 v0, v13, v0, vcc
	v_lshlrev_b32_e32 v0, 6, v0
	v_add_lshl_u32 v0, v0, v24, 2
	v_add_u32_e32 v133, s5, v0
	v_add_u32_e32 v134, s4, v0
	v_or_b32_e32 v0, 15, v23
	v_sub_u32_e32 v13, 63, v0
	v_cndmask_b32_e32 v0, v13, v0, vcc
	v_lshlrev_b32_e32 v0, 6, v0
	v_add_lshl_u32 v0, v0, v24, 2
	v_readlane_b32 s1, v254, 4
	v_readlane_b32 s3, v254, 5
	v_sub_u32_e32 v25, 63, v23
	v_add_u32_e32 v135, s5, v0
	v_add_u32_e32 v136, s4, v0
	v_and_b32_e32 v0, 0x1fc, v10
	v_add_u32_e32 v48, s1, v10
	v_add_u32_e32 v49, s3, v10
	v_cndmask_b32_e32 v25, v25, v23, vcc
	v_lshlrev_b32_e32 v37, 2, v37
	v_add_u32_e32 v137, s3, v0
	v_add_u32_e32 v138, s1, v0
	v_or_b32_e32 v10, 0x200, v0
	v_or_b32_e32 v0, 0x400, v0
	v_lshlrev_b32_e32 v25, 6, v25
	v_mul_lo_u32 v32, v32, s0
	v_mul_lo_u32 v33, v33, s0
	v_mul_lo_u32 v34, v34, s0
	v_mul_lo_u32 v17, v17, s0
	v_add_u32_e32 v92, s5, v37
	v_add_u32_e32 v93, s4, v37
	v_or_b32_e32 v37, v19, v21
	v_or_b32_e32 v21, v20, v21
	v_add_u32_e32 v140, s1, v10
	v_add_u32_e32 v142, s1, v0
	v_readlane_b32 s0, v251, 10
	v_add_lshl_u32 v25, v25, v24, 2
	v_mul_u32_u24_e32 v18, 0x104, v18
	v_lshlrev_b32_e32 v37, 2, v37
	v_lshlrev_b32_e32 v21, 2, v21
	v_add_u32_e32 v141, s3, v0
	s_add_i32 s0, s0, s2
	v_mov_b32_e32 v0, v1
	v_lshl_add_u32 v44, v27, 7, v16
	v_add_u32_e32 v51, s5, v25
	v_add_u32_e32 v94, s5, v37
	v_add_u32_e32 v95, s4, v37
	v_add_u32_e32 v96, s5, v21
	v_add_u32_e32 v97, s4, v21
	v_add_u32_e32 v106, s4, v25
	v_cmp_lt_i32_e64 s[38:39], 0, v22
	v_cmp_lt_i32_e64 s[40:41], 1, v22
	v_add_u32_e32 v139, s3, v10
	v_cmp_lt_i32_e64 s[42:43], 2, v22
	s_lshl_b32 s3, s0, 2
	s_mov_b32 s5, -1
	v_add_u32_e32 v143, v16, v32
	v_add_u32_e32 v144, v16, v33
	v_add_u32_e32 v145, v16, v34
	v_add_u32_e32 v146, v16, v17
	v_add_u32_e32 v147, v12, v35
	v_add_u32_e32 v148, v11, v36
	v_add_u32_e32 v149, v15, v18
	v_mov_b32_e32 v160, 0
	v_mov_b32_e32 v161, 0
	v_mov_b32_e32 v162, 0
	v_mov_b32_e32 v163, 0
	v_mov_b64_e32 v[34:35], v[0:1]
	v_mov_b64_e32 v[36:37], v[0:1]
	v_mov_b32_e32 v164, 0
	v_mov_b32_e32 v165, 0
	v_mov_b32_e32 v166, 0
	v_mov_b32_e32 v167, 0
	v_mov_b32_e32 v168, 0
	v_mov_b32_e32 v169, 0
	v_mov_b32_e32 v170, 0
	v_mov_b32_e32 v171, 0
	v_readlane_b32 s64, v251, 24
	v_readlane_b32 s65, v251, 25
	v_readlane_b32 s66, v251, 26
	v_readlane_b32 s67, v251, 27
	v_readlane_b32 s72, v251, 32
	v_readlane_b32 s73, v251, 33
	v_readlane_b32 s74, v251, 34
	v_readlane_b32 s75, v251, 35
	v_readlane_b32 s1, v251, 11
	s_waitcnt vmcnt(0)
	v_readfirstlane_b32 s0, v229
	s_lshr_b32 s0, s0, 6
	s_cmp_ge_u32 s0, 4
	s_cbranch_scc0 .Lprio_skip1
	s_setprio 1
.Lprio_skip1:
	s_branch .LBB0_200

; template <int PASS>
; __device__ void lru_items(const Params& p, unsigned char* shm, int l) {
;     bf16_t* xraw = (bf16_t*)shm;
;     float* xcf = (float*)(shm + 8704);
;     bf16_t* xcb = (bf16_t*)(shm + 25344);
;     bf16_t* wt = (bf16_t*)(shm + 34560);
;     float* As = (float*)(shm + 71424);
;     float* Bs = (float*)(shm + 104192);
;     float* Pq = (float*)(shm + 136960);
;     float* Hq = (float*)(shm + 139008);
;     const bf16_t* XL = (const bf16_t*)(p.ws + B_XL); bf16_t* GL = (bf16_t*)(p.ws + B_GL); const bf16_t* LWT = (const bf16_t*)(p.ws + SM_LWT);
;     float* SA = (float*)(p.ws + SM_SA); float* SH = (float*)(p.ws + SM_SH); const float* CIN = (const float*)(p.ws + SM_CIN);
;     const float* cw = p.in[4] + l * 4096; const float* cbias = p.in[5] + l * 1024;
;     const int tid = ltid(p.wave), lane = tid & 63, w = tid >> 6, fr = lane & 15, fq = lane >> 4, G_ = gridDim.x, total = NCHK * 16;
;     int n_loaded = -1;
;     float c0 = 0.f, c1 = 0.f, c2 = 0.f, c3 = 0.f, cb = 0.f, gba[4], gbx[4], gsp[4];
; #pragma unroll
;     for (int jt = 0; jt < 4; ++jt) { gba[jt] = 0.f; gbx[jt] = 0.f; gsp[jt] = 0.f; }
;     u32x4 xr0 = (u32x4){0u, 0u, 0u, 0u}, xr1 = (u32x4){0u, 0u, 0u, 0u};
;     ...
;     int it = lbid();
;     if (it < total) LRU_LOAD(it);
;     for (; it < total; it += G_) {
;         const int ck = it >> 4, n = it & 15, t0 = ck * 64;
;         *(u32x4*)(xraw + (tid >> 3) * 64 + (tid & 7) * 8) = xr0;
;         if (tid < 24) *(u32x4*)(xraw + (64 + (tid >> 3)) * 64 + (tid & 7) * 8) = xr1;
;         if (n != n_loaded) {
;             n_loaded = n;
; #pragma unroll
;             for (int i = 0; i < 4; ++i) { const int e = tid + 512 * i, mtx = e >> 9, rem = e & 511, j = rem >> 3, c8 = rem & 7;
;                 *(u32x4*)(wt + (mtx * 64 + j) * 72 + c8 * 8) = *(const u32x4*)(LWT + ((size_t)(mtx * 16 + n) * 64 + j) * 64 + c8 * 8); }
;             { const int ch = n * 64 + (tid & 63); c0 = cw[ch]; c1 = cw[1024 + ch]; c2 = cw[2048 + ch]; c3 = cw[3072 + ch]; cb = cbias[ch]; }
; #pragma unroll
;             for (int jt = 0; jt < 4; ++jt) { const int pi = (l * 2 + (w >> 2)) * 1024 + n * 64 + jt * 16 + fr; gba[jt] = p.in[7][pi]; gbx[jt] = p.in[9][pi]; gsp[jt] = -8.0f * log1pf(__expf(-p.in[10][pi])); }
;         }
;         u32x4 glv = (u32x4){0u, 0u, 0u, 0u}; float cin = 0.f;
;         const size_t go = (size_t)(t0 + (tid >> 3)) * 1024 + n * 64 + (tid & 7) * 8;
.LBB0_294:
	s_or_b64 exec, exec, s[0:1]
	v_readlane_b32 s0, v254, 43
	v_readlane_b32 s1, v254, 44
	s_mov_b32 s6, s0
	s_lshl_b32 s0, s0, 12
	s_ashr_i32 s1, s0, 31
	s_lshl_b32 s4, s6, 10
	v_readlane_b32 s60, v251, 20
	s_ashr_i32 s5, s4, 31
	s_lshl_b64 s[0:1], s[0:1], 2
	v_readlane_b32 s68, v251, 28
	v_readlane_b32 s69, v251, 29
	s_add_u32 s42, s68, s0
	v_readlane_b32 s70, v251, 30
	s_addc_u32 s43, s69, s1
	s_lshl_b64 s[0:1], s[4:5], 2
	v_readlane_b32 s71, v251, 31
	s_add_u32 s46, s70, s0
	s_addc_u32 s47, s71, s1
	v_lshlrev_b32_e32 v0, 3, v13
	v_bfe_u32 v19, v13, 3, 6
	v_readlane_b32 s0, v252, 11
	v_and_b32_e32 v28, 56, v0
	v_lshlrev_b32_e32 v0, 7, v19
	v_readlane_b32 s1, v252, 12
	v_lshlrev_b32_e32 v10, 1, v28
	v_mov_b32_e32 v11, v1
	v_lshl_add_u64 v[14:15], s[0:1], 0, v[0:1]
	v_lshlrev_b32_e32 v0, 2, v13
	v_add_u32_e32 v18, 0, v10
	v_lshl_add_u64 v[30:31], v[14:15], 0, v[10:11]
	v_and_b32_e32 v10, 0xfffffc00, v0
	v_and_b32_e32 v26, 63, v13
	v_and_b32_e32 v16, 15, v13
	v_lshl_add_u32 v10, s6, 11, v10
	s_movk_i32 s0, 0x80
	v_ashrrev_i32_e32 v17, 6, v13
	v_or_b32_e32 v42, v10, v16
	v_lshlrev_b32_e32 v10, 1, v26
	v_ashrrev_i32_e32 v15, 8, v13
	v_and_b32_e32 v22, 48, v13
	v_lshrrev_b32_e32 v24, 2, v13
	v_cmp_gt_i32_e64 s[38:39], s0, v13
	v_ashrrev_i32_e32 v32, 9, v13
	v_add_u32_e32 v33, 0x200, v13
	v_add_u32_e32 v34, 0x400, v13
	v_add_u32_e32 v35, 0x600, v13
	v_lshlrev_b32_e32 v13, 1, v13
	v_add_u32_e32 v11, 0, v10
	s_movk_i32 s1, 0x90
	v_ashrrev_i32_e32 v33, 9, v33
	v_ashrrev_i32_e32 v34, 9, v34
	v_ashrrev_i32_e32 v35, 9, v35
	v_and_b32_e32 v13, 0xffffff80, v13
	s_movk_i32 s0, 0x104
	v_and_b32_e32 v43, 1, v17
	v_lshlrev_b32_e32 v20, 4, v17
	v_lshlrev_b32_e32 v47, 4, v32
	v_lshl_or_b32 v32, v32, 6, v19
	v_lshlrev_b32_e32 v48, 4, v33
	v_lshl_or_b32 v33, v33, 6, v19
	v_lshlrev_b32_e32 v49, 4, v34
	v_lshl_or_b32 v34, v34, 6, v19
	v_lshlrev_b32_e32 v50, 4, v35
	v_lshl_or_b32 v19, v35, 6, v19
	v_add_u32_e32 v51, v11, v13
	v_add3_u32 v52, 0, v13, v10
	v_mul_lo_u32 v13, v17, s0
	v_mul_lo_u32 v35, v17, s1
	v_lshlrev_b32_e32 v17, 7, v17
	v_add_u32_e32 v36, 0x400, v17
	v_add_u32_e32 v53, v11, v36
	v_add3_u32 v54, 0, v36, v10
	v_add_u32_e32 v36, 0x800, v17
	v_and_b32_e32 v20, 48, v20
	v_add_u32_e32 v55, v11, v36
	v_add3_u32 v56, 0, v36, v10
	v_add_u32_e32 v36, 0xc00, v17
	v_or_b32_e32 v21, v20, v16
	v_add_u32_e32 v23, 0, v22
	v_add_u32_e32 v57, v11, v36
	v_add3_u32 v58, 0, v36, v10
	v_add_u32_e32 v36, 0x1000, v17
	v_mad_u32_u24 v44, v21, s1, v23
	v_lshl_or_b32 v21, v15, 7, v16
	v_and_or_b32 v20, v24, 12, v20
	v_lshlrev_b32_e32 v15, 12, v15
	v_add_u32_e32 v59, v11, v36
	v_add3_u32 v60, 0, v36, v10
	v_add_u32_e32 v36, 0x1400, v17
	v_add_u32_e32 v61, v11, v36
	v_add3_u32 v62, 0, v36, v10
	v_add_u32_e32 v36, 0x1800, v17
	v_add_u32_e32 v17, 0x1c00, v17
	v_lshl_or_b32 v15, v20, 6, v15
	v_add_u32_e32 v65, v11, v17
	v_add3_u32 v66, 0, v17, v10
	v_or_b32_e32 v17, v15, v16
	v_add_u32_e32 v14, v11, v10
	v_mul_lo_u32 v32, v32, s1
	v_mul_lo_u32 v33, v33, s1
	v_mul_lo_u32 v34, v34, s1
	v_mul_lo_u32 v19, v19, s1
	v_add3_u32 v64, 0, v36, v10
	v_mul_lo_u32 v10, v21, s1
	v_lshlrev_b32_e32 v17, 2, v17
	v_readlane_b32 s1, v254, 7
	v_readlane_b32 s0, v254, 6
	v_add3_u32 v68, 0, v10, v22
	v_add_u32_e32 v69, s1, v17
	v_add_u32_e32 v70, s0, v17
	v_or_b32_e32 v17, 64, v15
	v_or_b32_e32 v21, v17, v16
	v_lshlrev_b32_e32 v21, 2, v21
	v_add_u32_e32 v71, s1, v21
	v_add_u32_e32 v72, s0, v21
	v_or_b32_e32 v21, 0x80, v15
	v_or_b32_e32 v22, v21, v16
	v_lshlrev_b32_e32 v22, 2, v22
	v_add_u32_e32 v73, s1, v22
	v_add_u32_e32 v74, s0, v22
	v_or_b32_e32 v22, 0xc0, v15
	v_add_u32_e32 v67, v23, v10
	v_or_b32_e32 v23, v22, v16
	v_lshlrev_b32_e32 v23, 2, v23
	v_add_u32_e32 v75, s1, v23
	v_add_u32_e32 v76, s0, v23
	v_or_b32_e32 v23, 16, v16
	v_add_u32_e32 v63, v11, v36
	v_or_b32_e32 v36, v15, v23
	v_lshlrev_b32_e32 v36, 2, v36
	v_add_u32_e32 v77, s1, v36
	v_add_u32_e32 v78, s0, v36
	v_or_b32_e32 v36, v17, v23
	v_lshlrev_b32_e32 v36, 2, v36
	v_add_u32_e32 v79, s1, v36
	v_add_u32_e32 v80, s0, v36
	v_or_b32_e32 v36, v21, v23
	v_or_b32_e32 v23, v22, v23
	v_lshlrev_b32_e32 v23, 2, v23
	v_lshl_add_u32 v10, v16, 2, 0
	v_lshlrev_b32_e32 v36, 2, v36
	v_add_u32_e32 v83, s1, v23
	v_add_u32_e32 v84, s0, v23
	v_or_b32_e32 v23, 32, v16
	v_or_b32_e32 v16, 48, v16
	v_add_u32_e32 v81, s1, v36
	v_add_u32_e32 v82, s0, v36
	v_or_b32_e32 v36, v15, v23
	v_or_b32_e32 v15, v15, v16
	v_lshlrev_b32_e32 v15, 2, v15
	v_add_u32_e32 v93, s1, v15
	v_add_u32_e32 v94, s0, v15
	v_or_b32_e32 v15, v17, v16
	v_lshlrev_b32_e32 v15, 2, v15
	v_add_u32_e32 v95, s1, v15
	v_add_u32_e32 v96, s0, v15
	v_or_b32_e32 v15, v21, v16
	v_lshlrev_b32_e32 v15, 2, v15
	v_add_u32_e32 v97, s1, v15
	v_add_u32_e32 v98, s0, v15
	v_or_b32_e32 v15, v22, v16
	v_and_b32_e32 v24, -16, v12
	v_lshlrev_b32_e32 v15, 2, v15
	v_add_u32_e32 v99, s1, v15
	v_add_u32_e32 v100, s0, v15
	v_sub_u32_e32 v15, 63, v24
	v_cmp_eq_u32_e32 vcc, 0, v43
	v_lshl_or_b32 v25, v43, 12, v26
	v_lshl_add_u32 v29, v12, 7, v18
	v_cndmask_b32_e32 v15, v15, v24, vcc
	v_lshlrev_b32_e32 v15, 6, v15
	v_add_lshl_u32 v15, v15, v25, 2
	v_add_u32_e32 v101, s1, v15
	v_add_u32_e32 v102, s0, v15
	v_or_b32_e32 v15, 1, v24
	v_sub_u32_e32 v16, 63, v15
; __device__ __forceinline__ void unpack8(u32x4 w, f32x4& v0, f32x4& v1) { v0 = (f32x4){bflo(w.x), bfhi(w.x), bflo(w.y), bfhi(w.y)}; v1 = (f32x4){bflo(w.z), bfhi(w.z), bflo(w.w), bfhi(w.w)}; }
; template <int PASS>
; __device__ void lru_items(const Params& p, unsigned char* shm, int l) {
;     ...
;             const int seg = tid >> 7, d = (tid >> 6) & 1, j = tid & 63;
;             float h = 0.f, P = 1.f;
; #pragma unroll
;             for (int s = 0; s < 16; ++s) { const int st = seg * 16 + s, t = d ? 63 - st : st; const float a = As[(d * 64 + t) * 64 + j]; h = a * h + Bs[(d * 64 + t) * 64 + j]; P *= a; }
;             Pq[seg * 128 + (tid & 127)] = P; Hq[seg * 128 + (tid & 127)] = h;
;             __syncthreads();
;             if (PASS == 0) {
;                 if (tid < 128) { float hh = Hq[tid], PP = Pq[tid];
; #pragma unroll
;                     for (int q = 1; q < 4; ++q) { const float pq = Pq[q * 128 + tid]; hh = pq * hh + Hq[q * 128 + tid]; PP *= pq; }
;                     SA[so] = PP; SH[so] = hh; }
;             } else {
;                 float c = cin;
; #pragma unroll
;                 for (int q = 0; q < 3; ++q) if (q < seg) c = Pq[q * 128 + (tid & 127)] * c + Hq[q * 128 + (tid & 127)];
; #pragma unroll
;                 for (int s = 0; s < 16; ++s) { const int st = seg * 16 + s, t = d ? 63 - st : st; c = As[(d * 64 + t) * 64 + j] * c + Bs[(d * 64 + t) * 64 + j]; Bs[(d * 64 + t) * 64 + j] = c; }
;                 __syncthreads();
;                 const int t = tid >> 3, c8 = tid & 7;
;                 f32x4 g0, g1; unpack8(glv, g0, g1);
;                 const f32x4 f0 = *(const f32x4*)(Bs + t * 64 + c8 * 8), f1 = *(const f32x4*)(Bs + t * 64 + c8 * 8 + 4), r0 = *(const f32x4*)(Bs + (64 + t) * 64 + c8 * 8), r1 = *(const f32x4*)(Bs + (64 + t) * 64 + c8 * 8 + 4);
	v_cndmask_b32_e32 v15, v16, v15, vcc
	v_lshlrev_b32_e32 v15, 6, v15
	v_add_lshl_u32 v15, v15, v25, 2
	v_add_u32_e32 v103, s1, v15
	v_add_u32_e32 v104, s0, v15
	v_or_b32_e32 v15, 2, v24
	v_sub_u32_e32 v16, 63, v15
	v_cndmask_b32_e32 v15, v16, v15, vcc
	v_lshlrev_b32_e32 v15, 6, v15
	v_add_lshl_u32 v15, v15, v25, 2
	v_add_u32_e32 v105, s1, v15
	v_add_u32_e32 v106, s0, v15
	v_or_b32_e32 v15, 3, v24
	v_sub_u32_e32 v16, 63, v15
	v_cndmask_b32_e32 v15, v16, v15, vcc
	v_lshlrev_b32_e32 v15, 6, v15
	v_add_lshl_u32 v15, v15, v25, 2
	v_add_u32_e32 v107, s1, v15
	v_add_u32_e32 v108, s0, v15
	v_or_b32_e32 v15, 4, v24
	v_sub_u32_e32 v16, 63, v15
	v_cndmask_b32_e32 v15, v16, v15, vcc
	v_lshlrev_b32_e32 v15, 6, v15
	v_add_lshl_u32 v15, v15, v25, 2
	v_add_u32_e32 v109, s1, v15
	v_add_u32_e32 v110, s0, v15
	v_or_b32_e32 v15, 5, v24
	v_sub_u32_e32 v16, 63, v15
	v_cndmask_b32_e32 v15, v16, v15, vcc
	v_lshlrev_b32_e32 v15, 6, v15
	v_add_lshl_u32 v15, v15, v25, 2
	v_add_u32_e32 v111, s1, v15
	v_add_u32_e32 v112, s0, v15
	v_or_b32_e32 v15, 6, v24
	v_sub_u32_e32 v16, 63, v15
	v_cndmask_b32_e32 v15, v16, v15, vcc
	v_lshlrev_b32_e32 v15, 6, v15
	v_add_lshl_u32 v15, v15, v25, 2
	v_add_u32_e32 v113, s1, v15
	v_add_u32_e32 v114, s0, v15
	v_or_b32_e32 v15, 7, v24
	v_sub_u32_e32 v16, 63, v15
	v_cndmask_b32_e32 v15, v16, v15, vcc
	v_lshlrev_b32_e32 v15, 6, v15
	v_add_lshl_u32 v15, v15, v25, 2
	v_add_u32_e32 v115, s1, v15
	v_add_u32_e32 v116, s0, v15
	v_or_b32_e32 v15, 8, v24
	v_sub_u32_e32 v16, 63, v15
	v_cndmask_b32_e32 v15, v16, v15, vcc
	v_lshlrev_b32_e32 v15, 6, v15
	v_add_lshl_u32 v15, v15, v25, 2
	v_add_u32_e32 v117, s1, v15
	v_add_u32_e32 v118, s0, v15
	v_or_b32_e32 v15, 9, v24
	v_sub_u32_e32 v16, 63, v15
	v_cndmask_b32_e32 v15, v16, v15, vcc
	v_lshlrev_b32_e32 v15, 6, v15
	v_add_lshl_u32 v15, v15, v25, 2
	v_add_u32_e32 v119, s1, v15
	v_add_u32_e32 v120, s0, v15
	v_or_b32_e32 v15, 10, v24
	v_sub_u32_e32 v16, 63, v15
	v_cndmask_b32_e32 v15, v16, v15, vcc
	v_lshlrev_b32_e32 v15, 6, v15
	v_add_lshl_u32 v15, v15, v25, 2
	v_add_u32_e32 v121, s1, v15
	v_add_u32_e32 v122, s0, v15
	v_or_b32_e32 v15, 11, v24
	v_sub_u32_e32 v16, 63, v15
	v_cndmask_b32_e32 v15, v16, v15, vcc
	v_lshlrev_b32_e32 v15, 6, v15
	v_add_lshl_u32 v15, v15, v25, 2
	v_add_u32_e32 v123, s1, v15
	v_add_u32_e32 v124, s0, v15
	v_or_b32_e32 v15, 12, v24
	v_sub_u32_e32 v16, 63, v15
	v_cndmask_b32_e32 v15, v16, v15, vcc
	v_lshlrev_b32_e32 v15, 6, v15
	v_add_lshl_u32 v15, v15, v25, 2
	v_add_u32_e32 v125, s1, v15
	v_add_u32_e32 v126, s0, v15
	v_or_b32_e32 v15, 13, v24
	v_sub_u32_e32 v16, 63, v15
	v_cndmask_b32_e32 v15, v16, v15, vcc
	v_lshlrev_b32_e32 v15, 6, v15
	v_add_lshl_u32 v15, v15, v25, 2
	v_add_u32_e32 v127, s1, v15
	v_add_u32_e32 v128, s0, v15
	v_or_b32_e32 v15, 14, v24
	v_sub_u32_e32 v16, 63, v15
	v_cndmask_b32_e32 v15, v16, v15, vcc
	v_lshlrev_b32_e32 v15, 6, v15
	v_add_lshl_u32 v15, v15, v25, 2
	v_or_b32_e32 v12, 15, v12
	v_lshlrev_b32_e32 v36, 2, v36
	v_add_u32_e32 v129, s1, v15
	v_add_u32_e32 v131, s0, v15
	v_sub_u32_e32 v15, 63, v12
	v_add_u32_e32 v85, s1, v36
	v_add_u32_e32 v86, s0, v36
	v_or_b32_e32 v36, v17, v23
	v_cndmask_b32_e32 v12, v15, v12, vcc
	v_lshlrev_b32_e32 v36, 2, v36
	v_lshlrev_b32_e32 v12, 6, v12
	v_add_u32_e32 v87, s1, v36
	v_add_u32_e32 v88, s0, v36
	v_or_b32_e32 v36, v21, v23
	v_or_b32_e32 v23, v22, v23
	v_add_lshl_u32 v12, v12, v25, 2
	v_readlane_b32 s3, v254, 4
	v_readlane_b32 s4, v254, 5
	v_lshlrev_b32_e32 v36, 2, v36
	v_lshlrev_b32_e32 v23, 2, v23
	v_add_u32_e32 v132, s1, v12
	v_add_u32_e32 v133, s0, v12
	v_add_u32_e32 v12, 0x200, v0
	v_add_u32_e32 v45, s3, v0
	v_add_u32_e32 v46, s4, v0
	v_add_u32_e32 v89, s1, v36
	v_add_u32_e32 v90, s0, v36
	v_add_u32_e32 v91, s1, v23
	v_add_u32_e32 v92, s0, v23
	v_add_u32_e32 v134, s3, v12
	v_add_u32_e32 v135, s4, v12
	v_add_u32_e32 v12, 0x400, v0
	v_add_u32_e32 v0, 0x600, v0
	v_readlane_b32 s0, v251, 10
	v_mul_u32_u24_e32 v20, 0x104, v20
	v_add_u32_e32 v138, s3, v0
	v_add_u32_e32 v139, s4, v0
	s_add_i32 s0, s0, s2
	v_mov_b32_e32 v0, v1
	v_add_u32_e32 v136, s3, v12
	v_add_u32_e32 v137, s4, v12
	s_lshl_b32 s3, s0, 2
	s_mov_b32 s6, -1
	v_add_u32_e32 v141, v18, v32
	v_add_u32_e32 v142, v18, v33
	v_add_u32_e32 v143, v18, v34
	v_add_u32_e32 v144, v18, v19
	v_add_u32_e32 v145, v14, v13
	v_add_u32_e32 v146, v11, v35
	v_add_u32_e32 v147, v10, v20
	v_mov_b32_e32 v154, 0
	v_mov_b32_e32 v155, 0
	v_mov_b32_e32 v156, 0
	v_mov_b32_e32 v157, 0
	v_mov_b64_e32 v[32:33], v[0:1]
	v_mov_b64_e32 v[34:35], v[0:1]
	v_mov_b32_e32 v158, 0
	v_mov_b32_e32 v159, 0
	v_mov_b32_e32 v160, 0
	v_mov_b32_e32 v161, 0
	v_mov_b32_e32 v162, 0
	v_mov_b32_e32 v163, 0
	v_mov_b32_e32 v164, 0
	v_mov_b32_e32 v165, 0
	v_readlane_b32 s61, v251, 21
	v_readlane_b32 s62, v251, 22
	v_readlane_b32 s63, v251, 23
	v_readlane_b32 s64, v251, 24
	v_readlane_b32 s65, v251, 25
	v_readlane_b32 s66, v251, 26
	v_readlane_b32 s67, v251, 27
	v_readlane_b32 s72, v251, 32
	v_readlane_b32 s73, v251, 33
	v_readlane_b32 s74, v251, 34
	v_readlane_b32 s75, v251, 35
	v_readlane_b32 s1, v251, 11
	s_waitcnt vmcnt(0)
	v_readfirstlane_b32 s0, v229
	s_lshr_b32 s0, s0, 6
	s_cmp_ge_u32 s0, 4
	s_cbranch_scc0 .Lprio_skip2
	s_setprio 1

; __device__ __forceinline__ int lbid() { int b = blockIdx.x; asm volatile("" : "+s"(b)); return b; }
; __device__ void attn_items(const Params& p, unsigned char* shm) {
;     ...
;     const int tid = ltid(p.wave), lane = tid & 63, w = tid >> 6, fr = lane & 15, fq = lane >> 4, G_ = gridDim.x;
;     for (int i = tid; i < 24 * 129; i += 512) { const int hd = i / 129, j = i % 129; BT[hd * 132 + j] = p.in[21][(int)BUCKET[hd >> 3][j] * 24 + hd]; }
;     u32x4 kreg[5], vreg[5]; bf16x8 q0r, q1r;
;     const int total = 24 * 192;
;     int it = lbid();
;     ...
;     if (it < total) ATT_LOAD(it);
;     for (; it < total; it += G_) {
;         const AttnGeom G = attn_geom(it);
; #pragma unroll
;         for (int i = 0; i < 5; ++i) { const int e = tid + 512 * i, kk = e >> 3, c8 = e & 7;
;             if (e < 2176) {
;                 if (kk < 256) *(u32x4*)(Ks + kk * 72 + c8 * 8) = kreg[i];
; #pragma unroll
;                 for (int j = 0; j < 8; ++j) Vt[(c8 * 8 + j) * 320 + (kk ^ (c8 << 3))] = (bf16_t)((vreg[i][j >> 1] >> ((j & 1) * 16)) & 0xffffu); } }
;         const bf16x8 aq0 = q0r, aq1 = q1r;
;         __syncthreads();
;         if (it + G_ < total) ATT_LOAD(it + G_);
;         asm volatile("" ::: "memory");
;         const float* bs = BT + G.hd * 132;
;         f32x4 s[9];
; #pragma unroll
;         for (int kt = 0; kt < 9; ++kt) { const bf16_t* kr = Ks + (16 * w + 16 * kt + fr) * 72 + fq * 8;
;             f32x4 a = (f32x4){0.f, 0.f, 0.f, 0.f};
;             a = __builtin_amdgcn_mfma_f32_16x16x32_bf16(aq0, *(const bf16x8*)kr, a, 0, 0, 0);
;             a = __builtin_amdgcn_mfma_f32_16x16x32_bf16(aq1, *(const bf16x8*)(kr + 32), a, 0, 0, 0); s[kt] = a; }
;         float mx[4], ls[4];
; #pragma unroll
;         for (int i = 0; i < 4; ++i) { const int qi = fq * 4 + i; float m = -3.0e38f;
; #pragma unroll
;             for (int kt = 0; kt < 9; ++kt) { const int rel = 16 * kt + fr - 64 - qi, klat = G.q0 - 64 + 16 * w + 16 * kt + fr;
;                 const bool ok = rel >= -64 && rel <= 64 && klat >= 0 && klat < G.n_lat; const int bi = min(max(rel + 64, 0), 128);
;                 const float v = ok ? s[kt][i] + bs[bi] : -1.0e30f; s[kt][i] = v; m = fmaxf(m, v); }
;             m = fmaxf(m, __shfl_xor(m, 1)); m = fmaxf(m, __shfl_xor(m, 2)); m = fmaxf(m, __shfl_xor(m, 4)); m = fmaxf(m, __shfl_xor(m, 8));
.LBB0_338:
	v_and_b32_e32 v2, 63, v130
	s_movk_i32 s22, 0xc00
	s_andn2_b64 vcc, exec, s[40:41]
	s_cbranch_vccnz .LBB0_453
	v_and_b32_e32 v0, 48, v130
	v_and_b32_e32 v50, 64, v140
	v_add_u32_e32 v101, 0, v0
	v_xor_b32_e32 v0, 1, v140
	v_add_u32_e32 v50, 64, v50
	v_cmp_lt_i32_e32 vcc, v0, v50
	s_movk_i32 s0, 0x1500
	v_lshlrev_b32_e32 v99, 4, v47
	v_cndmask_b32_e32 v0, v140, v0, vcc
	v_lshlrev_b32_e32 v103, 2, v0
	v_xor_b32_e32 v0, 2, v140
	v_cmp_lt_i32_e32 vcc, v0, v50
	v_and_b32_e32 v92, 56, v48
	v_lshlrev_b32_e32 v51, 4, v46
	v_cndmask_b32_e32 v0, v140, v0, vcc
	v_lshlrev_b32_e32 v104, 2, v0
	v_xor_b32_e32 v0, 4, v140
	v_cmp_lt_i32_e32 vcc, v0, v50
	s_mov_b64 s[86:87], s[90:91]
	v_add_u32_e32 v61, 0x200, v130
	v_cndmask_b32_e32 v0, v140, v0, vcc
	v_lshlrev_b32_e32 v105, 2, v0
	v_xor_b32_e32 v0, 8, v140
	v_cmp_lt_i32_e32 vcc, v0, v50
	v_ashrrev_i32_e32 v110, 3, v61
	s_movk_i32 s1, 0x680
	v_cndmask_b32_e32 v0, v140, v0, vcc
	v_lshlrev_b32_e32 v106, 2, v0
	v_mul_lo_u32 v0, v47, s0
	v_readlane_b32 s0, v254, 9
	v_cmp_gt_i32_e64 s[42:43], s1, v130
	v_add_u32_e32 v63, 0x400, v130
	v_add_u32_e32 v47, s0, v0
	s_movk_i32 s0, 0x880
	v_cmp_gt_i32_e64 s[6:7], s0, v130
	s_movk_i32 s0, 0x100
	v_mul_u32_u24_e32 v0, 0x150, v93
	v_cmp_gt_i32_e64 s[8:9], s0, v98
	v_add3_u32 v107, v47, v0, v51
	v_lshlrev_b32_e32 v0, 1, v92
	v_writelane_b32 v255, s8, 10
	v_lshl_add_u64 v[94:95], s[90:91], 0, v[0:1]
	s_mov_b64 s[90:91], s[6:7]
	v_writelane_b32 v255, s9, 11
	s_and_b64 s[6:7], s[6:7], s[8:9]
	v_writelane_b32 v255, s6, 14
	v_cmp_gt_i32_e64 s[18:19], s0, v110
	v_ashrrev_i32_e32 v111, 3, v63
	v_writelane_b32 v255, s7, 15
	v_writelane_b32 v255, s18, 16
	s_and_b64 s[6:7], s[42:43], s[18:19]
	s_movk_i32 s1, 0x480
	v_writelane_b32 v255, s19, 17
	v_writelane_b32 v255, s6, 18
	v_cmp_gt_i32_e64 s[38:39], s0, v111
	v_cmp_gt_i32_e64 s[46:47], s1, v130
	v_writelane_b32 v255, s7, 19
	v_writelane_b32 v255, s38, 20
	v_add_u32_e32 v65, 0x600, v130
	s_and_b64 s[6:7], s[46:47], s[38:39]
	v_writelane_b32 v255, s39, 21
	v_ashrrev_i32_e32 v112, 3, v65
	v_writelane_b32 v255, s6, 22
	s_movk_i32 s3, 0x280
	v_cmp_gt_i32_e64 s[40:41], s0, v112
	v_writelane_b32 v255, s7, 23
	v_cmp_gt_i32_e64 s[50:51], s3, v130
	v_writelane_b32 v255, s40, 24
	v_add_u32_e32 v67, 0x800, v130
	s_and_b64 s[6:7], s[50:51], s[40:41]
	v_writelane_b32 v255, s41, 25
	v_ashrrev_i32_e32 v113, 3, v67
	s_movk_i32 s1, 0x80
	v_writelane_b32 v255, s6, 26
	v_cmp_gt_i32_e64 s[54:55], s1, v130
	v_cmp_gt_i32_e64 s[0:1], s0, v113
	v_writelane_b32 v255, s7, 27
	v_lshlrev_b32_e32 v48, 2, v46
	v_writelane_b32 v255, s0, 28
	v_sub_u32_e32 v115, v93, v48
	v_add_u32_e32 v76, 0x80, v115
	v_writelane_b32 v255, s1, 29
	s_and_b64 s[0:1], s[54:55], s[0:1]
	v_writelane_b32 v255, s0, 30
	v_or_b32_e32 v77, 2, v48
	v_sub_u32_e32 v118, v93, v77
	v_writelane_b32 v255, s1, 31
	s_movk_i32 s0, 0x81
	v_cmp_gt_u32_e64 s[6:7], s0, v115
	v_add_u32_e32 v119, 0x80, v118
	v_or_b32_e32 v108, v48, v99
	v_writelane_b32 v254, s6, 49
	v_lshl_add_u32 v50, v93, 1, v47
	v_lshlrev_b32_e32 v44, 3, v46
	v_writelane_b32 v254, s7, 50
	v_cmp_gt_u32_e64 s[6:7], s0, v76
	v_or_b32_e32 v76, 1, v48
	v_sub_u32_e32 v116, v93, v76
	v_writelane_b32 v254, s6, 37
	v_add_u32_e32 v117, 0x80, v116
	v_or_b32_e32 v48, 3, v48
	v_writelane_b32 v254, s7, 38
	v_cmp_gt_u32_e64 s[6:7], s0, v116
	v_sub_u32_e32 v120, v93, v48
	v_add_u32_e32 v121, 0x80, v120
	v_writelane_b32 v255, s6, 0
	v_add_u32_e32 v51, v44, v99
	v_mul_u32_u24_e32 v48, 0x540, v46
	v_writelane_b32 v255, s7, 1
	v_cmp_gt_u32_e64 s[6:7], s0, v117
	v_or_b32_e32 v127, 16, v93
	v_bitop3_b32 v78, v51, v127, 24 bitop3:0x78
	v_writelane_b32 v255, s6, 2
	v_or_b32_e32 v129, 32, v93
	v_bitop3_b32 v79, v51, v129, 40 bitop3:0x78
	v_writelane_b32 v255, s7, 3
	v_cmp_gt_u32_e64 s[6:7], s0, v118
	v_or_b32_e32 v132, 48, v93
	v_bitop3_b32 v80, v51, v132, 56 bitop3:0x78
	v_writelane_b32 v255, s6, 4
	v_and_b32_e32 v3, 7, v130
	v_lshlrev_b32_e32 v49, 3, v3
	v_writelane_b32 v255, s7, 5
	v_cmp_gt_u32_e64 s[6:7], s0, v119
	v_or_b32_e32 v100, v99, v93
	v_lshrrev_b32_e32 v109, 3, v2
	v_writelane_b32 v255, s6, 6
	s_movk_i32 s2, 0x90
	v_xor_b32_e32 v60, v49, v98
	v_writelane_b32 v255, s7, 7
; __device__ void attn_items(const Params& p, unsigned char* shm) {
;     ...
; #pragma unroll
;         for (int i = 0; i < 5; ++i) { const int e = tid + 512 * i, kk = e >> 3, c8 = e & 7;
;             if (e < 2176) {
;                 if (kk < 256) *(u32x4*)(Ks + kk * 72 + c8 * 8) = kreg[i];
; #pragma unroll
;                 for (int j = 0; j < 8; ++j) Vt[(c8 * 8 + j) * 320 + (kk ^ (c8 << 3))] = (bf16_t)((vreg[i][j >> 1] >> ((j & 1) * 16)) & 0xffffu); } }
;         const bf16x8 aq0 = q0r, aq1 = q1r;
;         __syncthreads();
;         if (it + G_ < total) ATT_LOAD(it + G_);
;         asm volatile("" ::: "memory");
;         const float* bs = BT + G.hd * 132;
;         f32x4 s[9];
; #pragma unroll
;         for (int kt = 0; kt < 9; ++kt) { const bf16_t* kr = Ks + (16 * w + 16 * kt + fr) * 72 + fq * 8;
;             f32x4 a = (f32x4){0.f, 0.f, 0.f, 0.f};
;             a = __builtin_amdgcn_mfma_f32_16x16x32_bf16(aq0, *(const bf16x8*)kr, a, 0, 0, 0);
;             a = __builtin_amdgcn_mfma_f32_16x16x32_bf16(aq1, *(const bf16x8*)(kr + 32), a, 0, 0, 0); s[kt] = a; }
;         float mx[4], ls[4];
; #pragma unroll
;         for (int i = 0; i < 4; ++i) { const int qi = fq * 4 + i; float m = -3.0e38f;
; #pragma unroll
;             for (int kt = 0; kt < 9; ++kt) { const int rel = 16 * kt + fr - 64 - qi, klat = G.q0 - 64 + 16 * w + 16 * kt + fr;
;                 const bool ok = rel >= -64 && rel <= 64 && klat >= 0 && klat < G.n_lat; const int bi = min(max(rel + 64, 0), 128);
;                 const float v = ok ? s[kt][i] + bs[bi] : -1.0e30f; s[kt][i] = v; m = fmaxf(m, v); }
;             m = fmaxf(m, __shfl_xor(m, 1)); m = fmaxf(m, __shfl_xor(m, 2)); m = fmaxf(m, __shfl_xor(m, 4)); m = fmaxf(m, __shfl_xor(m, 8));
;             float sum = 0.f;
; #pragma unroll
;             for (int kt = 0; kt < 9; ++kt) { const float pv = __expf(s[kt][i] - m); s[kt][i] = pv; sum += pv; }
;             sum += __shfl_xor(sum, 1); sum += __shfl_xor(sum, 2); sum += __shfl_xor(sum, 4); sum += __shfl_xor(sum, 8);
;             mx[i] = m; ls[i] = sum; }
;         bf16_t* Pw = Ps + w * 16 * 168;
; #pragma unroll
;         for (int i = 0; i < 4; ++i) {
; #pragma unroll
;             for (int kt = 0; kt < 9; ++kt) Pw[(fq * 4 + i) * 168 + 16 * kt + fr] = f2bf(s[kt][i]);
;             Pw[(fq * 4 + i) * 168 + 144 + fr] = 0; }
;         __syncthreads();
;         f32x4 o[4];
; #pragma unroll
	v_cmp_gt_u32_e64 s[6:7], s0, v120
	v_cmp_gt_u32_e64 s[0:1], s0, v121
	v_xor_b32_e32 v62, v110, v49
	v_writelane_b32 v255, s6, 12
	v_xor_b32_e32 v64, v111, v49
	v_xor_b32_e32 v66, v112, v49
	v_writelane_b32 v255, s7, 13
	v_writelane_b32 v255, s0, 8
	v_xor_b32_e32 v49, v113, v49
	v_mul_lo_u32 v114, v100, s2
	v_writelane_b32 v255, s1, 9
	s_movk_i32 s0, 0x540
	v_mad_u32_u24 v122, v46, s0, v50
	s_movk_i32 s0, 0x150
	v_mad_u32_u24 v77, v76, s0, s0
	v_add_u32_e32 v124, v50, v77
	v_mov_b32_e32 v77, 0x2a0
	v_mul_u32_u24_e32 v46, 0x150, v76
	v_mad_u32_u24 v123, v76, s0, v50
	v_mad_u32_u24 v76, v76, s0, v77
	v_add_u32_e32 v125, v50, v76
	v_mad_u32_u24 v76, v93, s3, 0
	v_bitop3_b32 v77, v51, v130, 8 bitop3:0x78
	v_lshl_add_u32 v126, v77, 1, v76
	v_add_u32_e32 v77, 0x2800, v76
	v_lshl_add_u32 v128, v78, 1, v77
	v_add_u32_e32 v78, 0x5000, v76
	v_lshl_add_u32 v131, v79, 1, v78
	v_add_u32_e32 v79, 0x7800, v76
	v_lshl_add_u32 v133, v80, 1, v79
	v_add_u32_e32 v80, 32, v51
	v_bitop3_b32 v81, v80, v130, 8 bitop3:0x78
	v_lshl_add_u32 v134, v81, 1, v76
	v_bitop3_b32 v81, v80, v127, 24 bitop3:0x78
	v_lshl_add_u32 v135, v81, 1, v77
	v_bitop3_b32 v81, v80, v129, 40 bitop3:0x78
	v_bitop3_b32 v80, v80, v132, 56 bitop3:0x78
	v_lshl_add_u32 v137, v80, 1, v79
	v_add_u32_e32 v80, 64, v51
	v_lshl_add_u32 v136, v81, 1, v78
	v_bitop3_b32 v81, v80, v130, 8 bitop3:0x78
	v_lshl_add_u32 v138, v81, 1, v76
	v_bitop3_b32 v81, v80, v127, 24 bitop3:0x78
	v_lshl_add_u32 v139, v81, 1, v77
	v_bitop3_b32 v81, v80, v129, 40 bitop3:0x78
	v_bitop3_b32 v80, v80, v132, 56 bitop3:0x78
	v_lshl_add_u32 v141, v80, 1, v79
	v_add_u32_e32 v80, 0x60, v51
	v_lshl_add_u32 v140, v81, 1, v78
	v_bitop3_b32 v81, v80, v130, 8 bitop3:0x78
	v_lshl_add_u32 v142, v81, 1, v76
	v_bitop3_b32 v81, v80, v127, 24 bitop3:0x78
	v_lshl_add_u32 v143, v81, 1, v77
	v_bitop3_b32 v81, v80, v129, 40 bitop3:0x78
	v_bitop3_b32 v80, v80, v132, 56 bitop3:0x78
	v_add_u32_e32 v51, 0x80, v51
	v_lshl_add_u32 v145, v80, 1, v79
	v_bitop3_b32 v80, v51, v130, 8 bitop3:0x78
	v_lshl_add_u32 v130, v80, 1, v76
	v_bitop3_b32 v76, v51, v127, 24 bitop3:0x78
	v_lshl_add_u32 v146, v76, 1, v77
	v_bitop3_b32 v76, v51, v129, 40 bitop3:0x78
	v_bitop3_b32 v51, v51, v132, 56 bitop3:0x78
	v_or_b32_e32 v149, 8, v109
	v_lshl_add_u32 v45, v3, 4, 0
	v_add_u32_e32 v47, v47, v0
	v_mul_u32_u24_e32 v0, 0x150, v109
	v_mul_lo_u32 v2, v98, s2
	v_lshl_add_u32 v60, v60, 1, 0
	v_mul_u32_u24_e32 v3, 0x1400, v3
	v_mul_lo_u32 v61, v110, s2
	v_lshl_add_u32 v62, v62, 1, 0
	v_mul_lo_u32 v63, v111, s2
	v_lshl_add_u32 v64, v64, 1, 0
	v_mul_lo_u32 v65, v112, s2
	v_lshl_add_u32 v66, v66, 1, 0
	v_mul_lo_u32 v67, v113, s2
	v_lshl_add_u32 v49, v49, 1, 0
	v_add_u32_e32 v68, 0x900, v114
	v_add_u32_e32 v69, 0x1200, v114
	v_add_u32_e32 v70, 0x1b00, v114
	v_add_u32_e32 v71, 0x2400, v114
	v_add_u32_e32 v72, 0x2d00, v114
	v_add_u32_e32 v73, 0x3600, v114
	v_add_u32_e32 v74, 0x3f00, v114
	v_add_u32_e32 v75, 0x4800, v114
	v_lshl_add_u32 v148, v51, 1, v79
	v_mul_u32_u24_e32 v51, 0x150, v149
	v_readlane_b32 s0, v251, 10
	s_movk_i32 s23, 0xff7f
	v_subrev_u32_e32 v102, 64, v99
	v_cmp_eq_u32_e64 s[36:37], 0, v93
	v_lshl_add_u32 v144, v81, 1, v78
	v_lshl_add_u32 v147, v76, 1, v78
	v_or_b32_e32 v150, 0x50, v93
	v_or_b32_e32 v151, 0x60, v93
	v_or_b32_e32 v152, 0x70, v93
	v_or_b32_e32 v153, 0x80, v93
	s_lshl_b32 s2, s4, 7
	s_movk_i32 s3, 0x80
	v_add_u32_e32 v154, v45, v2
	v_add_u32_e32 v155, v60, v3
	v_add_u32_e32 v156, v45, v61
	v_add_u32_e32 v157, v62, v3
	v_add_u32_e32 v158, v45, v63
	v_add_u32_e32 v159, v64, v3
	v_add_u32_e32 v160, v45, v65
	v_add_u32_e32 v161, v66, v3
	v_add_u32_e32 v162, v45, v67
	v_add_u32_e32 v163, v49, v3
	v_lshlrev_b32_e32 v96, 1, v44
	v_add_u32_e32 v164, v101, v68
	v_add_u32_e32 v165, v101, v69
	v_add_u32_e32 v166, v101, v70
	v_add_u32_e32 v167, v101, v71
	v_add_u32_e32 v168, v101, v72
	v_add_u32_e32 v169, v101, v73
	v_add_u32_e32 v170, v101, v74
	v_add_u32_e32 v171, v101, v75
	v_add_u32_e32 v172, v50, v48
	v_add_u32_e32 v173, v47, v0
	v_add_u32_e32 v174, v47, v51
	v_add_u32_e32 v175, v50, v46
	v_readlane_b32 s1, v251, 11
	v_readfirstlane_b32 s0, v229
	s_lshr_b32 s0, s0, 6
	s_cmp_ge_u32 s0, 4
	s_cbranch_scc0 .Lprio_skip3
	s_setprio 1

; __device__ __forceinline__ int ltid(int wave) { int t = (wave << 6) | (int)__builtin_amdgcn_mbcnt_hi(~0u, __builtin_amdgcn_mbcnt_lo(~0u, 0u)); asm volatile("" : "+v"(t)); return t; }
; __device__ __forceinline__ void xcd_barrier(const XcdBarrier& b, int wave) {
;     asm volatile("s_waitcnt vmcnt(0)" ::: "memory");
;     __syncthreads();
;     if (ltid(wave) == 0) {
;         unsigned* bar = b.bar;
;         __builtin_amdgcn_s_waitcnt(0);
;         unsigned nloc = b.st[0], nx = b.st[1];
;         if (nloc == 0u) { xcd_barrier_complete(bar, b.x, nloc, nx); b.st[0] = nloc; b.st[1] = nx; }
.LBB0_1054:
	s_setprio 0
	v_readlane_b32 s2, v252, 47
	v_readlane_b32 s3, v252, 48
	s_and_b64 vcc, exec, s[2:3]
	s_cbranch_vccz .LBB0_1104
	s_waitcnt vmcnt(0)
	v_mov_b32_e32 v0, v229
	s_waitcnt vmcnt(0) lgkmcnt(0)
	s_barrier
	s_nop 0
	v_cmp_eq_u32_e32 vcc, 0, v0
	s_and_saveexec_b64 s[20:21], vcc
	s_cbranch_execz .LBB0_1103
	v_readlane_b32 s0, v254, 10
	s_waitcnt vmcnt(0) expcnt(0) lgkmcnt(0)
	s_nop 0
	v_mov_b32_e32 v0, s0
	ds_read_b32 v3, v0
	v_readlane_b32 s0, v254, 11
	s_waitcnt lgkmcnt(0)
	v_cmp_ne_u32_e32 vcc, 0, v3
	v_mov_b32_e32 v0, s0
	ds_read_b32 v2, v0
	s_cbranch_vccnz .LBB0_1071
	s_mov_b32 s2, 1
	s_branch .LBB0_1059
